# mixer work list: next index claimed at start of each GLA pass-1 item (dequeue latency hidden)
# baseline (speedup 1.0000x reference)
.LBB0_169:
	s_movk_i32 s0, 0x900
	s_waitcnt lgkmcnt(0)
	v_cmp_gt_i32_e32 vcc, s0, v0
	s_or_b64 s[6:7], s[6:7], exec
	s_and_saveexec_b64 s[34:35], vcc
	s_cbranch_execz .LBB0_168
	v_readfirstlane_b32 s0, v0
	s_cmpk_ge_u32 s0, 0x300
	s_cselect_b32 s2, 1, 0
	v_mov_b32_e32 v251, s2
	s_cbranch_scc0 .Ldq_nopf
	v_cmp_eq_u32_e32 vcc, 0, v167
	s_and_saveexec_b64 s[2:3], vcc
	v_readlane_b32 s0, v247, 49
	v_readlane_b32 s1, v247, 50
	v_mov_b32_e32 v250, 1
	s_nop 3
	global_atomic_add v250, v153, v250, s[0:1] sc0
	s_mov_b64 exec, s[2:3]
.Ldq_nopf:
	s_movk_i32 s0, 0x7f
	v_cmp_lt_i32_e32 vcc, s0, v0
	s_and_saveexec_b64 s[0:1], vcc
	s_xor_b64 s[8:9], exec, s[0:1]
	s_cbranch_execz .LBB0_184
	s_movk_i32 s0, 0xff
	v_cmp_lt_u32_e32 vcc, s0, v0
	s_and_saveexec_b64 s[0:1], vcc
	s_xor_b64 s[10:11], exec, s[0:1]
	s_cbranch_execz .LBB0_181
	s_movk_i32 s0, 0x1ff
	v_cmp_lt_u32_e32 vcc, s0, v0
	s_and_saveexec_b64 s[0:1], vcc
	s_xor_b64 s[0:1], exec, s[0:1]
	s_cbranch_execz .LBB0_178
	v_cmp_lt_u32_e32 vcc, s99, v0
	s_and_saveexec_b64 s[2:3], vcc
	s_xor_b64 s[2:3], exec, s[2:3]
	v_add_u32_e32 v1, 0xfffffd00, v0
	v_lshrrev_b32_e32 v12, 3, v1
	v_bfe_u32 v10, v0, 1, 2
	s_or_saveexec_b64 s[14:15], s[2:3]
	v_and_b32_e32 v13, 1, v0
	v_mov_b32_e32 v16, 0
	s_mov_b64 s[2:3], 0
	s_xor_b64 exec, exec, s[14:15]
	v_add_u32_e32 v1, 0xfffffe00, v0
	v_bfe_u32 v0, v0, 1, 3
	s_mov_b64 s[2:3], exec
	v_lshrrev_b32_e32 v10, 4, v1
	v_mov_b32_e32 v12, 1
	v_mov_b32_e32 v16, v13
	v_mov_b32_e32 v13, v0
	s_or_b64 exec, exec, s[14:15]

.LBB0_325:
	s_or_b64 exec, exec, s[14:15]
	v_mov_b32_e32 v0, v167
	s_barrier
	s_nop 0
	v_cmp_eq_u32_e32 vcc, 0, v0
	s_and_saveexec_b64 s[0:1], vcc
	s_xor_b64 s[0:1], exec, s[0:1]
	s_cbranch_execz .LBB0_167
	s_mov_b64 s[8:9], exec
	v_mbcnt_lo_u32_b32 v0, s8, 0
	v_mbcnt_hi_u32_b32 v0, s9, v0
	v_cmp_eq_u32_e32 vcc, 0, v0
	s_and_saveexec_b64 s[2:3], vcc
	s_cbranch_execz .LBB0_166
	s_waitcnt vmcnt(0)
	v_cmp_ne_u32_e32 vcc, 0, v251
	s_cbranch_vccz .Ldq_claim
	v_mov_b32_e32 v1, v250
	s_branch .LBB0_166
.Ldq_claim:
	s_bcnt1_i32_b64 s8, s[8:9]
	v_mov_b32_e32 v1, s8
	v_readlane_b32 s8, v247, 49
	v_readlane_b32 s9, v247, 50
	s_nop 4
	global_atomic_add v1, v153, v1, s[8:9] sc0
	s_branch .LBB0_166

	.amdhsa_kernel _Z9trunk_fwd6Params
		.amdhsa_group_segment_fixed_size 81920
		.amdhsa_private_segment_fixed_size 0
		.amdhsa_kernarg_size 536
		.amdhsa_user_sgpr_count 2
		.amdhsa_user_sgpr_dispatch_ptr 0
		.amdhsa_user_sgpr_queue_ptr 0
		.amdhsa_user_sgpr_kernarg_segment_ptr 1
		.amdhsa_user_sgpr_dispatch_id 0
		.amdhsa_user_sgpr_kernarg_preload_length 0
		.amdhsa_user_sgpr_kernarg_preload_offset 0
		.amdhsa_user_sgpr_private_segment_size 0
		.amdhsa_uses_dynamic_stack 0
		.amdhsa_enable_private_segment 0
		.amdhsa_system_sgpr_workgroup_id_x 1
		.amdhsa_system_sgpr_workgroup_id_y 0
		.amdhsa_system_sgpr_workgroup_id_z 0
		.amdhsa_system_sgpr_workgroup_info 0
		.amdhsa_system_vgpr_workitem_id 2
		.amdhsa_next_free_vgpr 252
		.amdhsa_next_free_sgpr 102
		.amdhsa_accum_offset 252
		.amdhsa_reserve_vcc 1
		.amdhsa_float_round_mode_32 0
		.amdhsa_float_round_mode_16_64 0
		.amdhsa_float_denorm_mode_32 3
		.amdhsa_float_denorm_mode_16_64 3
		.amdhsa_dx10_clamp 1
		.amdhsa_ieee_mode 1
		.amdhsa_fp16_overflow 0
		.amdhsa_tg_split 0
		.amdhsa_exception_fp_ieee_invalid_op 0
		.amdhsa_exception_fp_denorm_src 0
		.amdhsa_exception_fp_ieee_div_zero 0
		.amdhsa_exception_fp_ieee_overflow 0
		.amdhsa_exception_fp_ieee_underflow 0
		.amdhsa_exception_fp_ieee_inexact 0
		.amdhsa_exception_int_div_zero 0
	.end_amdhsa_kernel

amdhsa.kernels:
  - .agpr_count:     0
    .args:
      - .offset:         0
        .size:           280
        .value_kind:     by_value
      - .offset:         280
        .size:           4
        .value_kind:     hidden_block_count_x
      - .offset:         284
        .size:           4
        .value_kind:     hidden_block_count_y
      - .offset:         288
        .size:           4
        .value_kind:     hidden_block_count_z
      - .offset:         292
        .size:           2
        .value_kind:     hidden_group_size_x
      - .offset:         294
        .size:           2
        .value_kind:     hidden_group_size_y
      - .offset:         296
        .size:           2
        .value_kind:     hidden_group_size_z
      - .offset:         298
        .size:           2
        .value_kind:     hidden_remainder_x
      - .offset:         300
        .size:           2
        .value_kind:     hidden_remainder_y
      - .offset:         302
        .size:           2
        .value_kind:     hidden_remainder_z
      - .offset:         320
        .size:           8
        .value_kind:     hidden_global_offset_x
      - .offset:         328
        .size:           8
        .value_kind:     hidden_global_offset_y
      - .offset:         336
        .size:           8
        .value_kind:     hidden_global_offset_z
      - .offset:         344
        .size:           2
        .value_kind:     hidden_grid_dims
      - .offset:         368
        .size:           8
        .value_kind:     hidden_multigrid_sync_arg
    .group_segment_fixed_size: 81920
    .kernarg_segment_align: 8
    .kernarg_segment_size: 536
    .language:       OpenCL C
    .language_version:
      - 2
      - 0
    .max_flat_workgroup_size: 256
    .name:           _Z9trunk_fwd6Params
    .private_segment_fixed_size: 0
    .sgpr_count:     108
    .sgpr_spill_count: 195
    .symbol:         _Z9trunk_fwd6Params.kd
    .uniform_work_group_size: 1
    .uses_dynamic_stack: false
    .vgpr_count:     252
    .vgpr_spill_count: 0
    .wavefront_size: 64
